# static s_setprio 2 during GEMM k-loops for workgroups with odd (blockIdx>>3), so co-resident workgroups do not share MFMA issue evenly
# speedup vs baseline: 1.0672x; 1.0072x over previous
.LBB0_59:
	s_and_b32 s2, s2, 7
	v_readlane_b32 s4, v251, 7
	s_or_b32 s11, s2, s4
	s_lshl_b32 s10, s16, 7
	s_mul_i32 s2, s11, 0x160000
	s_add_u32 s4, s18, s2
	v_readlane_b32 s72, v250, 53
	s_addc_u32 s5, s19, 0
	s_mul_i32 s2, s16, 0xb0000
	v_readlane_b32 s84, v249, 1
	v_mov_b32_e32 v56, v200
	s_add_u32 s6, s84, s2
	s_movk_i32 s2, 0xb00
	v_ashrrev_i32_e32 v57, 2, v56
	v_lshlrev_b32_e32 v0, 3, v56
	s_waitcnt vmcnt(0)
	v_and_b32_e32 v188, 24, v0
	v_mad_i64_i32 v[0:1], s[8:9], v57, s2, 0
	v_lshlrev_b64 v[178:179], 1, v[0:1]
	v_add_u32_e32 v0, 64, v57
	v_mad_i64_i32 v[0:1], s[8:9], v0, s2, 0
	s_mul_hi_u32 s7, s10, 0x1600
	v_readlane_b32 s85, v249, 2
	v_lshlrev_b64 v[180:181], 1, v[0:1]
	v_add_u32_e32 v0, 0x80, v57
	s_addc_u32 s7, s85, s7
	v_lshlrev_b32_e32 v196, 1, v188
	v_mad_i64_i32 v[44:45], s[8:9], v0, s2, 0
	v_add_u32_e32 v0, 0xc0, v57
	v_lshl_add_u64 v[176:177], s[4:5], 0, v[196:197]
	v_mad_i64_i32 v[48:49], s[8:9], v0, s2, 0
	v_lshl_add_u64 v[182:183], s[6:7], 0, v[196:197]
	v_lshl_add_u64 v[40:41], v[176:177], 0, v[178:179]
	v_lshl_add_u64 v[42:43], v[176:177], 0, v[180:181]
	v_lshl_add_u64 v[46:47], v[44:45], 1, v[176:177]
	v_lshl_add_u64 v[50:51], v[48:49], 1, v[176:177]
	v_lshl_add_u64 v[52:53], v[182:183], 0, v[178:179]
	v_lshl_add_u64 v[54:55], v[182:183], 0, v[180:181]
	v_and_b32_e32 v192, 63, v200
	v_readfirstlane_b32 s44, v200
	v_lshrrev_b32_e32 v193, 2, v192
	v_and_b32_e32 v194, 3, v192
	v_lshrrev_b32_e32 v201, 4, v192
	s_lshr_b32 s44, s44, 6
	v_xor_b32_e32 v206, v194, v201
	v_lshlrev_b32_e32 v206, 4, v206
	s_lshl_b32 s32, s44, 6
	v_add_u32_e32 v212, s32, v193
	v_mul_u32_u24_e32 v212, 0x1600, v212
	v_add_u32_e32 v234, v212, v206
	v_add_u32_e32 v235, 0x16000, v234
	v_add_u32_e32 v236, 0x2c000, v234
	v_add_u32_e32 v237, 0x42000, v234
	s_lshl_b32 s32, s44, 5
	v_add_u32_e32 v212, s32, v193
	v_mul_u32_u24_e32 v212, 0x1600, v212
	v_add_u32_e32 v238, v212, v206
	v_add_u32_e32 v239, 0x16000, v238
	v_and_b32_e32 v193, 31, v192
	v_lshrrev_b32_e32 v194, 5, v192
	v_bfe_u32 v201, v192, 2, 2
	v_xor_b32_e32 v206, v194, v201
	v_lshlrev_b32_e32 v206, 4, v206
	v_lshl_add_u32 v206, v193, 6, v206
	s_lshr_b32 s32, s44, 1
	s_lshl_b32 s32, s32, 13
	v_add_u32_e32 v240, s32, v206
	v_xor_b32_e32 v241, 32, v240
	s_and_b32 s32, s44, 1
	s_lshl_b32 s32, s32, 12
	s_add_u32 s32, s32, 0x4000
	v_add_u32_e32 v242, s32, v206
	v_xor_b32_e32 v243, 32, v242
	s_lshl_b32 s46, s44, 12
	s_lshl_b32 s47, s44, 11
	s_add_u32 s47, s47, 0x4000
	s_mov_b32 s40, s4
	s_mov_b32 s41, s5
	s_mov_b32 s42, s6
	s_mov_b32 s43, s7
	s_add_u32 m0, s46, 0x0
	s_nop 0
	global_load_lds_dwordx4 v234, s[40:41]
	s_add_u32 m0, m0, 0x400
	s_nop 0
	global_load_lds_dwordx4 v235, s[40:41]
	s_add_u32 m0, m0, 0x400
	s_nop 0
	global_load_lds_dwordx4 v236, s[40:41]
	s_add_u32 m0, m0, 0x400
	s_nop 0
	global_load_lds_dwordx4 v237, s[40:41]
	s_add_u32 m0, s47, 0x0
	s_nop 0
	global_load_lds_dwordx4 v238, s[42:43]
	s_add_u32 m0, m0, 0x400
	s_nop 0
	global_load_lds_dwordx4 v239, s[42:43]
	s_add_u32 s40, s40, 64
	s_addc_u32 s41, s41, 0
	s_add_u32 s42, s42, 64
	s_addc_u32 s43, s43, 0
	s_add_u32 m0, s46, 0x6000
	s_nop 0
	global_load_lds_dwordx4 v234, s[40:41]
	s_add_u32 m0, m0, 0x400
	s_nop 0
	global_load_lds_dwordx4 v235, s[40:41]
	s_add_u32 m0, m0, 0x400
	s_nop 0
	global_load_lds_dwordx4 v236, s[40:41]
	s_add_u32 m0, m0, 0x400
	s_nop 0
	global_load_lds_dwordx4 v237, s[40:41]
	s_add_u32 m0, s47, 0x6000
	s_nop 0
	global_load_lds_dwordx4 v238, s[42:43]
	s_add_u32 m0, m0, 0x400
	s_nop 0
	global_load_lds_dwordx4 v239, s[42:43]
	s_add_u32 s40, s40, 64
	s_addc_u32 s41, s41, 0
	s_add_u32 s42, s42, 64
	s_addc_u32 s43, s43, 0
	s_mov_b32 s45, 0xc000
	s_mov_b32 s49, 0
	v_and_b32_e32 v58, 0xfffff9f, v56
	v_lshrrev_b32_e32 v59, 1, v56
	v_and_b32_e32 v56, 0x5f, v56
	s_movk_i32 s2, 0x50
	v_and_b32_e32 v59, 16, v59
	v_mad_u32_u24 v56, v56, s2, 0
	v_mul_lo_u32 v57, v57, s2
	v_mul_lo_u32 v58, v58, s2
	v_add_u32_e32 v189, v56, v59
	v_add_u32_e32 v56, 0, v196
	v_mov_b32_e32 v0, 0
	v_add_u32_e32 v58, 0, v58
	v_add_u32_e32 v191, v56, v57
	s_mov_b32 s17, 64
	s_mov_b32 s18, 0
	v_mov_b32_e32 v1, v0
	v_mov_b32_e32 v2, v0
	v_mov_b32_e32 v3, v0
	v_mov_b32_e32 v4, v0
	v_mov_b32_e32 v5, v0
	v_mov_b32_e32 v6, v0
	v_mov_b32_e32 v7, v0
	v_mov_b32_e32 v8, v0
	v_mov_b32_e32 v9, v0
	v_mov_b32_e32 v10, v0
	v_mov_b32_e32 v11, v0
	v_mov_b32_e32 v12, v0
	v_mov_b32_e32 v13, v0
	v_mov_b32_e32 v14, v0
	v_mov_b32_e32 v15, v0
	v_lshlrev_b64 v[184:185], 1, v[44:45]
	v_lshlrev_b64 v[186:187], 1, v[48:49]
	v_add_u32_e32 v190, v58, v59
	v_mov_b32_e32 v40, v0
	v_mov_b32_e32 v41, v0
	v_mov_b32_e32 v42, v0
	v_mov_b32_e32 v43, v0
	v_mov_b32_e32 v44, v0
	v_mov_b32_e32 v45, v0
	v_mov_b32_e32 v46, v0
	v_mov_b32_e32 v47, v0
	v_mov_b32_e32 v16, v0
	v_mov_b32_e32 v17, v0
	v_mov_b32_e32 v18, v0
	v_mov_b32_e32 v19, v0
	v_mov_b32_e32 v20, v0
	v_mov_b32_e32 v21, v0
	v_mov_b32_e32 v22, v0
	v_mov_b32_e32 v23, v0
	v_mov_b32_e32 v24, v0
	v_mov_b32_e32 v25, v0
	v_mov_b32_e32 v26, v0
	v_mov_b32_e32 v27, v0
	v_mov_b32_e32 v28, v0
	v_mov_b32_e32 v29, v0
	v_mov_b32_e32 v30, v0
	v_mov_b32_e32 v31, v0
	v_mov_b32_e32 v32, v0
	v_mov_b32_e32 v33, v0
	v_mov_b32_e32 v34, v0
	v_mov_b32_e32 v35, v0
	v_mov_b32_e32 v36, v0
	v_mov_b32_e32 v37, v0
	v_mov_b32_e32 v38, v0
	v_mov_b32_e32 v39, v0
	v_mov_b32_e32 v48, v0
	v_mov_b32_e32 v49, v0
	v_mov_b32_e32 v50, v0
	v_mov_b32_e32 v51, v0
	v_mov_b32_e32 v52, v0
	v_mov_b32_e32 v53, v0
	v_mov_b32_e32 v54, v0
	v_mov_b32_e32 v55, v0
	v_mov_b32_e32 v56, v0
	v_mov_b32_e32 v57, v0
	v_mov_b32_e32 v58, v0
	v_mov_b32_e32 v59, v0
	v_mov_b32_e32 v60, v0
	v_mov_b32_e32 v61, v0
	v_mov_b32_e32 v62, v0
	v_mov_b32_e32 v63, v0
	v_mov_b32_e32 v64, v0
	v_mov_b32_e32 v65, v0
	v_mov_b32_e32 v66, v0
	v_mov_b32_e32 v67, v0
	v_mov_b32_e32 v68, v0
	v_mov_b32_e32 v69, v0
	v_mov_b32_e32 v70, v0
	v_mov_b32_e32 v71, v0
	v_mov_b32_e32 v72, v0
	v_mov_b32_e32 v73, v0
	v_mov_b32_e32 v74, v0
	v_mov_b32_e32 v75, v0
	v_mov_b32_e32 v76, v0
	v_mov_b32_e32 v77, v0
	v_mov_b32_e32 v78, v0
	v_mov_b32_e32 v79, v0
	v_mov_b32_e32 v80, v0
	v_mov_b32_e32 v81, v0
	v_mov_b32_e32 v82, v0
	v_mov_b32_e32 v83, v0
	v_mov_b32_e32 v84, v0
	v_mov_b32_e32 v85, v0
	v_mov_b32_e32 v86, v0
	v_mov_b32_e32 v87, v0
	v_mov_b32_e32 v88, v0
	v_mov_b32_e32 v89, v0
	v_mov_b32_e32 v90, v0
	v_mov_b32_e32 v91, v0
	v_mov_b32_e32 v92, v0
	v_mov_b32_e32 v93, v0
	v_mov_b32_e32 v94, v0
	v_mov_b32_e32 v95, v0
	v_mov_b32_e32 v96, v0
	v_mov_b32_e32 v97, v0
	v_mov_b32_e32 v98, v0
	v_mov_b32_e32 v99, v0
	v_mov_b32_e32 v100, v0
	v_mov_b32_e32 v101, v0
	v_mov_b32_e32 v102, v0
	v_mov_b32_e32 v103, v0
	v_mov_b32_e32 v104, v0
	v_mov_b32_e32 v105, v0
	v_mov_b32_e32 v106, v0
	v_mov_b32_e32 v107, v0
	v_mov_b32_e32 v108, v0
	v_mov_b32_e32 v109, v0
	v_mov_b32_e32 v110, v0
	v_mov_b32_e32 v111, v0
	v_mov_b32_e32 v112, v0
	v_mov_b32_e32 v113, v0
	v_mov_b32_e32 v114, v0
	v_mov_b32_e32 v115, v0
	v_mov_b32_e32 v116, v0
	v_mov_b32_e32 v117, v0
	v_mov_b32_e32 v118, v0
	v_mov_b32_e32 v119, v0
	v_mov_b32_e32 v120, v0
	v_mov_b32_e32 v121, v0
	v_mov_b32_e32 v122, v0
	v_mov_b32_e32 v123, v0
	v_mov_b32_e32 v124, v0
	v_mov_b32_e32 v125, v0
	v_mov_b32_e32 v126, v0
	v_mov_b32_e32 v127, v0
	v_readlane_b32 s73, v250, 54
	v_readlane_b32 s74, v250, 55
	v_readlane_b32 s75, v250, 56
	v_readlane_b32 s76, v250, 57
	v_readlane_b32 s77, v250, 58
	v_readlane_b32 s78, v250, 59
	v_readlane_b32 s79, v250, 60
	v_readlane_b32 s80, v250, 61
	v_readlane_b32 s81, v250, 62
	v_readlane_b32 s82, v250, 63
	v_readlane_b32 s83, v249, 0
	v_readlane_b32 s86, v249, 3
	v_readlane_b32 s87, v249, 4
	s_waitcnt vmcnt(6)
	s_waitcnt lgkmcnt(0)
	v_readlane_b32 s44, v251, 5
	s_nop 0
	s_bitcmp1_b32 s44, 5
	s_cbranch_scc0 .Lnoprio_1
	s_setprio 2
.Lnoprio_1:
	s_barrier
	s_branch .LBB0_61

.Lp8_tail:
	ds_read_b128 v[128:131], v242
	ds_read_b128 v[136:139], v240
	ds_read_b128 v[132:135], v242 offset:2048
	ds_read_b128 v[140:143], v240 offset:2048
	ds_read_b128 v[144:147], v240 offset:4096
	ds_read_b128 v[148:151], v240 offset:6144
	ds_read_b128 v[152:155], v243
	ds_read_b128 v[156:159], v243 offset:2048
	ds_read_b128 v[160:163], v241
	ds_read_b128 v[164:167], v241 offset:2048
	ds_read_b128 v[168:171], v241 offset:4096
	ds_read_b128 v[172:175], v241 offset:6144
	s_waitcnt lgkmcnt(10)
	v_mfma_f32_32x32x16_bf16 v[112:127], v[128:131], v[136:139], v[112:127]
	s_waitcnt lgkmcnt(9)
	v_mfma_f32_32x32x16_bf16 v[96:111], v[132:135], v[136:139], v[96:111]
	s_waitcnt lgkmcnt(8)
	v_mfma_f32_32x32x16_bf16 v[80:95], v[128:131], v[140:143], v[80:95]
	v_mfma_f32_32x32x16_bf16 v[64:79], v[132:135], v[140:143], v[64:79]
	s_waitcnt lgkmcnt(7)
	v_mfma_f32_32x32x16_bf16 v[48:63], v[128:131], v[144:147], v[48:63]
	v_mfma_f32_32x32x16_bf16 v[32:47], v[132:135], v[144:147], v[32:47]
	s_waitcnt lgkmcnt(6)
	v_mfma_f32_32x32x16_bf16 v[16:31], v[128:131], v[148:151], v[16:31]
	v_mfma_f32_32x32x16_bf16 v[0:15], v[132:135], v[148:151], v[0:15]
	s_waitcnt lgkmcnt(3)
	v_mfma_f32_32x32x16_bf16 v[112:127], v[152:155], v[160:163], v[112:127]
	v_mfma_f32_32x32x16_bf16 v[96:111], v[156:159], v[160:163], v[96:111]
	s_waitcnt lgkmcnt(2)
	v_mfma_f32_32x32x16_bf16 v[80:95], v[152:155], v[164:167], v[80:95]
	v_mfma_f32_32x32x16_bf16 v[64:79], v[156:159], v[164:167], v[64:79]
	s_waitcnt lgkmcnt(1)
	v_mfma_f32_32x32x16_bf16 v[48:63], v[152:155], v[168:171], v[48:63]
	s_mov_b32 s32, 0x6000
	s_cmp_eq_u32 s49, 0xc000
	s_cselect_b32 s32, 0xffff4000, s32
	s_add_u32 s49, s49, s32
	v_add_u32_e32 v240, s32, v240
	v_add_u32_e32 v241, s32, v241
	v_add_u32_e32 v242, s32, v242
	v_add_u32_e32 v243, s32, v243
	v_mfma_f32_32x32x16_bf16 v[32:47], v[156:159], v[168:171], v[32:47]
	s_waitcnt lgkmcnt(0)
	v_mfma_f32_32x32x16_bf16 v[16:31], v[152:155], v[172:175], v[16:31]
	v_mfma_f32_32x32x16_bf16 v[0:15], v[156:159], v[172:175], v[0:15]
	s_add_u32 s18, s18, 1
	s_waitcnt vmcnt(0)
	s_cmp_lt_u32 s18, 88
	s_barrier
	s_cbranch_scc1 .Lp8_tail
	s_setprio 0
	s_branch .LBB0_63

.LBB0_75:
	s_and_b32 s4, s2, 7
	v_readlane_b32 s5, v251, 7
	s_or_b32 s11, s4, s5
	v_readlane_b32 s16, v250, 53
	s_lshr_b32 s10, s2, 3
	s_lshl_b32 s2, s11, 19
	v_readlane_b32 s22, v250, 59
	v_mov_b32_e32 v13, v200
	v_readlane_b32 s23, v250, 60
	s_add_u32 s4, s22, s2
	v_readlane_b32 s26, v250, 63
	v_ashrrev_i32_e32 v38, 2, v13
	v_lshlrev_b32_e32 v0, 3, v13
	s_addc_u32 s5, s23, 0
	s_lshl_b32 s2, s10, 18
	s_waitcnt vmcnt(0)
	v_and_b32_e32 v188, 24, v0
	v_add_u32_e32 v46, 0x80, v38
	v_readlane_b32 s27, v249, 0
	s_add_u32 s6, s26, s2
	v_lshlrev_b32_e32 v196, 1, v188
	v_add_u32_e32 v42, 64, v38
	v_ashrrev_i32_e32 v47, 31, v46
	v_add_u32_e32 v50, 0xc0, v38
	s_addc_u32 s7, s27, 0
	v_lshl_add_u64 v[176:177], s[4:5], 0, v[196:197]
	v_ashrrev_i32_e32 v39, 31, v38
	v_ashrrev_i32_e32 v43, 31, v42
	v_lshlrev_b64 v[4:5], 11, v[46:47]
	v_ashrrev_i32_e32 v51, 31, v50
	v_lshlrev_b64 v[0:1], 11, v[38:39]
	v_lshlrev_b64 v[2:3], 11, v[42:43]
	v_lshl_add_u64 v[48:49], v[176:177], 0, v[4:5]
	v_lshlrev_b64 v[4:5], 11, v[50:51]
	v_lshl_add_u64 v[178:179], s[6:7], 0, v[196:197]
	v_lshl_add_u64 v[40:41], v[176:177], 0, v[0:1]
	v_lshl_add_u64 v[44:45], v[176:177], 0, v[2:3]
	v_lshl_add_u64 v[52:53], v[176:177], 0, v[4:5]
	v_lshl_add_u64 v[54:55], v[178:179], 0, v[0:1]
	v_lshl_add_u64 v[56:57], v[178:179], 0, v[2:3]
	v_and_b32_e32 v192, 63, v200
	v_readfirstlane_b32 s44, v200
	v_lshrrev_b32_e32 v193, 2, v192
	v_and_b32_e32 v194, 3, v192
	v_lshrrev_b32_e32 v201, 4, v192
	s_lshr_b32 s44, s44, 6
	v_xor_b32_e32 v206, v194, v201
	v_lshlrev_b32_e32 v206, 4, v206
	s_lshl_b32 s32, s44, 6
	v_add_u32_e32 v212, s32, v193
	v_lshlrev_b32_e32 v212, 11, v212
	v_add_u32_e32 v234, v212, v206
	v_add_u32_e32 v235, 0x8000, v234
	v_add_u32_e32 v236, 0x10000, v234
	v_add_u32_e32 v237, 0x18000, v234
	s_lshl_b32 s32, s44, 5
	v_add_u32_e32 v212, s32, v193
	v_lshlrev_b32_e32 v212, 11, v212
	v_add_u32_e32 v238, v212, v206
	v_add_u32_e32 v239, 0x8000, v238
	v_and_b32_e32 v193, 31, v192
	v_lshrrev_b32_e32 v194, 5, v192
	v_bfe_u32 v201, v192, 2, 2
	v_xor_b32_e32 v206, v194, v201
	v_lshlrev_b32_e32 v206, 4, v206
	v_lshl_add_u32 v206, v193, 6, v206
	s_lshr_b32 s32, s44, 1
	s_lshl_b32 s32, s32, 13
	v_add_u32_e32 v240, s32, v206
	v_xor_b32_e32 v241, 32, v240
	s_and_b32 s32, s44, 1
	s_lshl_b32 s32, s32, 12
	s_add_u32 s32, s32, 0x4000
	v_add_u32_e32 v242, s32, v206
	v_xor_b32_e32 v243, 32, v242
	s_lshl_b32 s46, s44, 12
	s_lshl_b32 s47, s44, 11
	s_add_u32 s47, s47, 0x4000
	s_mov_b32 s40, s4
	s_mov_b32 s41, s5
	s_mov_b32 s42, s6
	s_mov_b32 s43, s7
	s_add_u32 m0, s46, 0x0
	s_nop 0
	global_load_lds_dwordx4 v234, s[40:41]
	s_add_u32 m0, m0, 0x400
	s_nop 0
	global_load_lds_dwordx4 v235, s[40:41]
	s_add_u32 m0, m0, 0x400
	s_nop 0
	global_load_lds_dwordx4 v236, s[40:41]
	s_add_u32 m0, m0, 0x400
	s_nop 0
	global_load_lds_dwordx4 v237, s[40:41]
	s_add_u32 m0, s47, 0x0
	s_nop 0
	global_load_lds_dwordx4 v238, s[42:43]
	s_add_u32 m0, m0, 0x400
	s_nop 0
	global_load_lds_dwordx4 v239, s[42:43]
	s_add_u32 s40, s40, 64
	s_addc_u32 s41, s41, 0
	s_add_u32 s42, s42, 64
	s_addc_u32 s43, s43, 0
	s_add_u32 m0, s46, 0x6000
	s_nop 0
	global_load_lds_dwordx4 v234, s[40:41]
	s_add_u32 m0, m0, 0x400
	s_nop 0
	global_load_lds_dwordx4 v235, s[40:41]
	s_add_u32 m0, m0, 0x400
	s_nop 0
	global_load_lds_dwordx4 v236, s[40:41]
	s_add_u32 m0, m0, 0x400
	s_nop 0
	global_load_lds_dwordx4 v237, s[40:41]
	s_add_u32 m0, s47, 0x6000
	s_nop 0
	global_load_lds_dwordx4 v238, s[42:43]
	s_add_u32 m0, m0, 0x400
	s_nop 0
	global_load_lds_dwordx4 v239, s[42:43]
	s_add_u32 s40, s40, 64
	s_addc_u32 s41, s41, 0
	s_add_u32 s42, s42, 64
	s_addc_u32 s43, s43, 0
	s_mov_b32 s45, 0xc000
	s_mov_b32 s49, 0
	v_and_b32_e32 v58, 0xfffff9f, v13
	v_lshrrev_b32_e32 v59, 1, v13
	v_and_b32_e32 v13, 0x5f, v13
	s_movk_i32 s2, 0x50
	v_and_b32_e32 v59, 16, v59
	v_mad_u32_u24 v13, v13, s2, 0
	v_mul_lo_u32 v60, v38, s2
	v_mul_lo_u32 v58, v58, s2
	v_add_u32_e32 v189, v13, v59
	v_add_u32_e32 v13, 0, v196
	v_readlane_b32 s17, v250, 54
	v_mov_b32_e32 v0, 0
	v_lshlrev_b64 v[38:39], 10, v[38:39]
	v_add_u32_e32 v58, 0, v58
	v_lshlrev_b64 v[42:43], 10, v[42:43]
	v_lshlrev_b64 v[46:47], 10, v[46:47]
	v_lshlrev_b64 v[50:51], 10, v[50:51]
	v_add_u32_e32 v191, v13, v60
	s_mov_b32 s16, 64
	s_mov_b32 s17, 0
	v_mov_b32_e32 v1, v0
	v_mov_b32_e32 v2, v0
	v_mov_b32_e32 v3, v0
	v_mov_b32_e32 v4, v0
	v_mov_b32_e32 v5, v0
	v_mov_b32_e32 v6, v0
	v_mov_b32_e32 v7, v0
	v_mov_b32_e32 v8, v0
	v_mov_b32_e32 v9, v0
	v_mov_b32_e32 v10, v0
	v_mov_b32_e32 v11, v0
	v_mov_b32_e32 v12, v0
	v_lshlrev_b64 v[180:181], 1, v[38:39]
	v_add_u32_e32 v190, v58, v59
	v_lshlrev_b64 v[182:183], 1, v[42:43]
	v_lshlrev_b64 v[184:185], 1, v[46:47]
	v_lshlrev_b64 v[186:187], 1, v[50:51]
	v_mov_b32_e32 v13, v0
	v_mov_b32_e32 v38, v0
	v_mov_b32_e32 v39, v0
	v_mov_b32_e32 v14, v0
	v_mov_b32_e32 v15, v0
	v_mov_b32_e32 v16, v0
	v_mov_b32_e32 v17, v0
	v_mov_b32_e32 v18, v0
	v_mov_b32_e32 v19, v0
	v_mov_b32_e32 v20, v0
	v_mov_b32_e32 v21, v0
	v_mov_b32_e32 v22, v0
	v_mov_b32_e32 v23, v0
	v_mov_b32_e32 v24, v0
	v_mov_b32_e32 v25, v0
	v_mov_b32_e32 v26, v0
	v_mov_b32_e32 v27, v0
	v_mov_b32_e32 v28, v0
	v_mov_b32_e32 v29, v0
	v_mov_b32_e32 v30, v0
	v_mov_b32_e32 v31, v0
	v_mov_b32_e32 v32, v0
	v_mov_b32_e32 v33, v0
	v_mov_b32_e32 v34, v0
	v_mov_b32_e32 v35, v0
	v_mov_b32_e32 v36, v0
	v_mov_b32_e32 v37, v0
	v_mov_b32_e32 v40, v0
	v_mov_b32_e32 v41, v0
	v_mov_b32_e32 v42, v0
	v_mov_b32_e32 v43, v0
	v_mov_b32_e32 v44, v0
	v_mov_b32_e32 v45, v0
	v_mov_b32_e32 v46, v0
	v_mov_b32_e32 v47, v0
	v_mov_b32_e32 v48, v0
	v_mov_b32_e32 v49, v0
	v_mov_b32_e32 v50, v0
	v_mov_b32_e32 v51, v0
	v_mov_b32_e32 v52, v0
	v_mov_b32_e32 v53, v0
	v_mov_b32_e32 v54, v0
	v_mov_b32_e32 v55, v0
	v_mov_b32_e32 v56, v0
	v_mov_b32_e32 v57, v0
	v_mov_b32_e32 v58, v0
	v_mov_b32_e32 v59, v0
	v_mov_b32_e32 v60, v0
	v_mov_b32_e32 v61, v0
	v_mov_b32_e32 v62, v0
	v_mov_b32_e32 v63, v0
	v_mov_b32_e32 v64, v0
	v_mov_b32_e32 v65, v0
	v_mov_b32_e32 v66, v0
	v_mov_b32_e32 v67, v0
	v_mov_b32_e32 v68, v0
	v_mov_b32_e32 v69, v0
	v_mov_b32_e32 v70, v0
	v_mov_b32_e32 v71, v0
	v_mov_b32_e32 v72, v0
	v_mov_b32_e32 v73, v0
	v_mov_b32_e32 v74, v0
	v_mov_b32_e32 v75, v0
	v_mov_b32_e32 v76, v0
	v_mov_b32_e32 v77, v0
	v_mov_b32_e32 v78, v0
	v_mov_b32_e32 v79, v0
	v_mov_b32_e32 v80, v0
	v_mov_b32_e32 v81, v0
	v_mov_b32_e32 v82, v0
	v_mov_b32_e32 v83, v0
	v_mov_b32_e32 v84, v0
	v_mov_b32_e32 v85, v0
	v_mov_b32_e32 v86, v0
	v_mov_b32_e32 v87, v0
	v_mov_b32_e32 v88, v0
	v_mov_b32_e32 v89, v0
	v_mov_b32_e32 v90, v0
	v_mov_b32_e32 v91, v0
	v_mov_b32_e32 v92, v0
	v_mov_b32_e32 v93, v0
	v_mov_b32_e32 v94, v0
	v_mov_b32_e32 v95, v0
	v_mov_b32_e32 v96, v0
	v_mov_b32_e32 v97, v0
	v_mov_b32_e32 v98, v0
	v_mov_b32_e32 v99, v0
	v_mov_b32_e32 v100, v0
	v_mov_b32_e32 v101, v0
	v_mov_b32_e32 v102, v0
	v_mov_b32_e32 v103, v0
	v_mov_b32_e32 v104, v0
	v_mov_b32_e32 v105, v0
	v_mov_b32_e32 v106, v0
	v_mov_b32_e32 v107, v0
	v_mov_b32_e32 v108, v0
	v_mov_b32_e32 v109, v0
	v_mov_b32_e32 v110, v0
	v_mov_b32_e32 v111, v0
	v_mov_b32_e32 v112, v0
	v_mov_b32_e32 v113, v0
	v_mov_b32_e32 v114, v0
	v_mov_b32_e32 v115, v0
	v_mov_b32_e32 v116, v0
	v_mov_b32_e32 v117, v0
	v_mov_b32_e32 v118, v0
	v_mov_b32_e32 v119, v0
	v_mov_b32_e32 v120, v0
	v_mov_b32_e32 v121, v0
	v_mov_b32_e32 v122, v0
	v_mov_b32_e32 v123, v0
	v_mov_b32_e32 v124, v0
	v_mov_b32_e32 v125, v0
	v_mov_b32_e32 v126, v0
	v_mov_b32_e32 v127, v0
	v_readlane_b32 s18, v250, 55
	v_readlane_b32 s19, v250, 56
	v_readlane_b32 s20, v250, 57
	v_readlane_b32 s21, v250, 58
	v_readlane_b32 s24, v250, 61
	v_readlane_b32 s25, v250, 62
	v_readlane_b32 s28, v249, 1
	v_readlane_b32 s29, v249, 2
	v_readlane_b32 s30, v249, 3
	v_readlane_b32 s31, v249, 4
	s_waitcnt vmcnt(6)
	s_waitcnt lgkmcnt(0)
	v_readlane_b32 s44, v251, 5
	s_nop 0
	s_bitcmp1_b32 s44, 5
	s_cbranch_scc0 .Lnoprio_0
	s_setprio 2

.Lp7_tail:
	ds_read_b128 v[128:131], v242
	ds_read_b128 v[136:139], v240
	ds_read_b128 v[132:135], v242 offset:2048
	ds_read_b128 v[140:143], v240 offset:2048
	ds_read_b128 v[144:147], v240 offset:4096
	ds_read_b128 v[148:151], v240 offset:6144
	ds_read_b128 v[152:155], v243
	ds_read_b128 v[156:159], v243 offset:2048
	ds_read_b128 v[160:163], v241
	ds_read_b128 v[164:167], v241 offset:2048
	ds_read_b128 v[168:171], v241 offset:4096
	ds_read_b128 v[172:175], v241 offset:6144
	s_waitcnt lgkmcnt(10)
	v_mfma_f32_32x32x16_bf16 v[112:127], v[128:131], v[136:139], v[112:127]
	s_waitcnt lgkmcnt(9)
	v_mfma_f32_32x32x16_bf16 v[96:111], v[132:135], v[136:139], v[96:111]
	s_waitcnt lgkmcnt(8)
	v_mfma_f32_32x32x16_bf16 v[80:95], v[128:131], v[140:143], v[80:95]
	v_mfma_f32_32x32x16_bf16 v[64:79], v[132:135], v[140:143], v[64:79]
	s_waitcnt lgkmcnt(7)
	v_mfma_f32_32x32x16_bf16 v[48:63], v[128:131], v[144:147], v[48:63]
	v_mfma_f32_32x32x16_bf16 v[32:47], v[132:135], v[144:147], v[32:47]
	s_waitcnt lgkmcnt(6)
	v_mfma_f32_32x32x16_bf16 v[16:31], v[128:131], v[148:151], v[16:31]
	v_mfma_f32_32x32x16_bf16 v[0:15], v[132:135], v[148:151], v[0:15]
	s_waitcnt lgkmcnt(3)
	v_mfma_f32_32x32x16_bf16 v[112:127], v[152:155], v[160:163], v[112:127]
	v_mfma_f32_32x32x16_bf16 v[96:111], v[156:159], v[160:163], v[96:111]
	s_waitcnt lgkmcnt(2)
	v_mfma_f32_32x32x16_bf16 v[80:95], v[152:155], v[164:167], v[80:95]
	v_mfma_f32_32x32x16_bf16 v[64:79], v[156:159], v[164:167], v[64:79]
	s_waitcnt lgkmcnt(1)
	v_mfma_f32_32x32x16_bf16 v[48:63], v[152:155], v[168:171], v[48:63]
	s_mov_b32 s32, 0x6000
	s_cmp_eq_u32 s49, 0xc000
	s_cselect_b32 s32, 0xffff4000, s32
	s_add_u32 s49, s49, s32
	v_add_u32_e32 v240, s32, v240
	v_add_u32_e32 v241, s32, v241
	v_add_u32_e32 v242, s32, v242
	v_add_u32_e32 v243, s32, v243
	v_mfma_f32_32x32x16_bf16 v[32:47], v[156:159], v[168:171], v[32:47]
	s_waitcnt lgkmcnt(0)
	v_mfma_f32_32x32x16_bf16 v[16:31], v[152:155], v[172:175], v[16:31]
	v_mfma_f32_32x32x16_bf16 v[0:15], v[156:159], v[172:175], v[0:15]
	s_add_u32 s17, s17, 1
	s_waitcnt vmcnt(0)
	s_cmp_lt_u32 s17, 32
	s_barrier
	s_cbranch_scc1 .Lp7_tail
	s_setprio 0
	s_branch .LBB0_74

.LBB0_106:
	s_and_b32 s2, s2, 7
	v_readlane_b32 s4, v251, 7
	s_or_b32 s16, s2, s4
	s_lshl_b32 s4, s15, 7
	s_lshl_b32 s14, s16, 19
	v_mov_b32_e32 v56, v200
	s_add_u32 s6, s20, s14
	s_mov_b32 s5, s3
	s_addc_u32 s7, s21, 0
	v_ashrrev_i32_e32 v36, 2, v56
	v_lshlrev_b32_e32 v0, 3, v56
	s_lshl_b64 s[8:9], s[4:5], 11
	v_readlane_b32 s10, v249, 19
	s_waitcnt vmcnt(0)
	v_and_b32_e32 v188, 24, v0
	v_add_u32_e32 v44, 0x80, v36
	v_readlane_b32 s11, v249, 20
	s_add_u32 s8, s10, s8
	v_lshlrev_b32_e32 v196, 1, v188
	v_add_u32_e32 v40, 64, v36
	v_ashrrev_i32_e32 v45, 31, v44
	v_add_u32_e32 v48, 0xc0, v36
	s_addc_u32 s9, s11, s9
	v_lshl_add_u64 v[176:177], s[6:7], 0, v[196:197]
	v_ashrrev_i32_e32 v37, 31, v36
	v_ashrrev_i32_e32 v41, 31, v40
	v_lshlrev_b64 v[4:5], 11, v[44:45]
	v_ashrrev_i32_e32 v49, 31, v48
	v_lshlrev_b64 v[0:1], 11, v[36:37]
	v_lshlrev_b64 v[2:3], 11, v[40:41]
	v_lshl_add_u64 v[46:47], v[176:177], 0, v[4:5]
	v_lshlrev_b64 v[4:5], 11, v[48:49]
	v_lshl_add_u64 v[178:179], s[8:9], 0, v[196:197]
	v_lshl_add_u64 v[38:39], v[176:177], 0, v[0:1]
	v_lshl_add_u64 v[42:43], v[176:177], 0, v[2:3]
	v_lshl_add_u64 v[50:51], v[176:177], 0, v[4:5]
	v_lshl_add_u64 v[52:53], v[178:179], 0, v[0:1]
	v_lshl_add_u64 v[54:55], v[178:179], 0, v[2:3]
	v_and_b32_e32 v192, 63, v200
	v_readfirstlane_b32 s44, v200
	v_lshrrev_b32_e32 v193, 2, v192
	v_and_b32_e32 v194, 3, v192
	v_lshrrev_b32_e32 v201, 4, v192
	s_lshr_b32 s44, s44, 6
	v_xor_b32_e32 v206, v194, v201
	v_lshlrev_b32_e32 v206, 4, v206
	s_lshl_b32 s32, s44, 6
	v_add_u32_e32 v212, s32, v193
	v_lshlrev_b32_e32 v212, 11, v212
	v_add_u32_e32 v234, v212, v206
	v_add_u32_e32 v235, 0x8000, v234
	v_add_u32_e32 v236, 0x10000, v234
	v_add_u32_e32 v237, 0x18000, v234
	s_lshl_b32 s32, s44, 5
	v_add_u32_e32 v212, s32, v193
	v_lshlrev_b32_e32 v212, 11, v212
	v_add_u32_e32 v238, v212, v206
	v_add_u32_e32 v239, 0x8000, v238
	v_and_b32_e32 v193, 31, v192
	v_lshrrev_b32_e32 v194, 5, v192
	v_bfe_u32 v201, v192, 2, 2
	v_xor_b32_e32 v206, v194, v201
	v_lshlrev_b32_e32 v206, 4, v206
	v_lshl_add_u32 v206, v193, 6, v206
	s_lshr_b32 s32, s44, 1
	s_lshl_b32 s32, s32, 13
	v_add_u32_e32 v240, s32, v206
	v_xor_b32_e32 v241, 32, v240
	s_and_b32 s32, s44, 1
	s_lshl_b32 s32, s32, 12
	s_add_u32 s32, s32, 0x4000
	v_add_u32_e32 v242, s32, v206
	v_xor_b32_e32 v243, 32, v242
	s_lshl_b32 s46, s44, 12
	s_lshl_b32 s47, s44, 11
	s_add_u32 s47, s47, 0x4000
	s_mov_b32 s40, s6
	s_mov_b32 s41, s7
	s_mov_b32 s42, s8
	s_mov_b32 s43, s9
	s_add_u32 m0, s46, 0x0
	s_nop 0
	global_load_lds_dwordx4 v234, s[40:41]
	s_add_u32 m0, m0, 0x400
	s_nop 0
	global_load_lds_dwordx4 v235, s[40:41]
	s_add_u32 m0, m0, 0x400
	s_nop 0
	global_load_lds_dwordx4 v236, s[40:41]
	s_add_u32 m0, m0, 0x400
	s_nop 0
	global_load_lds_dwordx4 v237, s[40:41]
	s_add_u32 m0, s47, 0x0
	s_nop 0
	global_load_lds_dwordx4 v238, s[42:43]
	s_add_u32 m0, m0, 0x400
	s_nop 0
	global_load_lds_dwordx4 v239, s[42:43]
	s_add_u32 s40, s40, 64
	s_addc_u32 s41, s41, 0
	s_add_u32 s42, s42, 64
	s_addc_u32 s43, s43, 0
	s_add_u32 m0, s46, 0x6000
	s_nop 0
	global_load_lds_dwordx4 v234, s[40:41]
	s_add_u32 m0, m0, 0x400
	s_nop 0
	global_load_lds_dwordx4 v235, s[40:41]
	s_add_u32 m0, m0, 0x400
	s_nop 0
	global_load_lds_dwordx4 v236, s[40:41]
	s_add_u32 m0, m0, 0x400
	s_nop 0
	global_load_lds_dwordx4 v237, s[40:41]
	s_add_u32 m0, s47, 0x6000
	s_nop 0
	global_load_lds_dwordx4 v238, s[42:43]
	s_add_u32 m0, m0, 0x400
	s_nop 0
	global_load_lds_dwordx4 v239, s[42:43]
	s_add_u32 s40, s40, 64
	s_addc_u32 s41, s41, 0
	s_add_u32 s42, s42, 64
	s_addc_u32 s43, s43, 0
	s_mov_b32 s45, 0xc000
	s_mov_b32 s49, 0
	v_and_b32_e32 v57, 0xfffff9f, v56
	v_lshrrev_b32_e32 v58, 1, v56
	v_and_b32_e32 v56, 0x5f, v56
	s_movk_i32 s2, 0x50
	v_and_b32_e32 v58, 16, v58
	v_mad_u32_u24 v56, v56, s2, 0
	v_mul_lo_u32 v59, v36, s2
	v_mul_lo_u32 v57, v57, s2
	v_add_u32_e32 v189, v56, v58
	v_add_u32_e32 v56, 0, v196
	v_mov_b32_e32 v0, 0
	v_lshlrev_b64 v[36:37], 10, v[36:37]
	v_add_u32_e32 v57, 0, v57
	v_lshlrev_b64 v[40:41], 10, v[40:41]
	v_lshlrev_b64 v[44:45], 10, v[44:45]
	v_lshlrev_b64 v[48:49], 10, v[48:49]
	v_add_u32_e32 v191, v56, v59
	s_mov_b32 s5, 64
	s_mov_b32 s17, 0
	v_mov_b32_e32 v1, v0
	v_mov_b32_e32 v2, v0
	v_mov_b32_e32 v3, v0
	v_mov_b32_e32 v4, v0
	v_mov_b32_e32 v5, v0
	v_mov_b32_e32 v6, v0
	v_mov_b32_e32 v7, v0
	v_mov_b32_e32 v8, v0
	v_mov_b32_e32 v9, v0
	v_mov_b32_e32 v10, v0
	v_mov_b32_e32 v11, v0
	v_lshlrev_b64 v[180:181], 1, v[36:37]
	v_add_u32_e32 v190, v57, v58
	v_lshlrev_b64 v[182:183], 1, v[40:41]
	v_lshlrev_b64 v[184:185], 1, v[44:45]
	v_lshlrev_b64 v[186:187], 1, v[48:49]
	v_mov_b32_e32 v36, v0
	v_mov_b32_e32 v37, v0
	v_mov_b32_e32 v38, v0
	v_mov_b32_e32 v39, v0
	v_mov_b32_e32 v40, v0
	v_mov_b32_e32 v41, v0
	v_mov_b32_e32 v42, v0
	v_mov_b32_e32 v12, v0
	v_mov_b32_e32 v13, v0
	v_mov_b32_e32 v14, v0
	v_mov_b32_e32 v15, v0
	v_mov_b32_e32 v16, v0
	v_mov_b32_e32 v17, v0
	v_mov_b32_e32 v18, v0
	v_mov_b32_e32 v19, v0
	v_mov_b32_e32 v20, v0
	v_mov_b32_e32 v21, v0
	v_mov_b32_e32 v22, v0
	v_mov_b32_e32 v23, v0
	v_mov_b32_e32 v24, v0
	v_mov_b32_e32 v25, v0
	v_mov_b32_e32 v26, v0
	v_mov_b32_e32 v27, v0
	v_mov_b32_e32 v28, v0
	v_mov_b32_e32 v29, v0
	v_mov_b32_e32 v30, v0
	v_mov_b32_e32 v31, v0
	v_mov_b32_e32 v32, v0
	v_mov_b32_e32 v33, v0
	v_mov_b32_e32 v34, v0
	v_mov_b32_e32 v35, v0
	v_mov_b32_e32 v43, v0
	v_mov_b32_e32 v44, v0
	v_mov_b32_e32 v45, v0
	v_mov_b32_e32 v46, v0
	v_mov_b32_e32 v47, v0
	v_mov_b32_e32 v48, v0
	v_mov_b32_e32 v49, v0
	v_mov_b32_e32 v50, v0
	v_mov_b32_e32 v51, v0
	v_mov_b32_e32 v52, v0
	v_mov_b32_e32 v53, v0
	v_mov_b32_e32 v54, v0
	v_mov_b32_e32 v55, v0
	v_mov_b32_e32 v56, v0
	v_mov_b32_e32 v57, v0
	v_mov_b32_e32 v58, v0
	v_mov_b32_e32 v59, v0
	v_mov_b32_e32 v60, v0
	v_mov_b32_e32 v61, v0
	v_mov_b32_e32 v62, v0
	v_mov_b32_e32 v63, v0
	v_mov_b32_e32 v64, v0
	v_mov_b32_e32 v65, v0
	v_mov_b32_e32 v66, v0
	v_mov_b32_e32 v67, v0
	v_mov_b32_e32 v68, v0
	v_mov_b32_e32 v69, v0
	v_mov_b32_e32 v70, v0
	v_mov_b32_e32 v71, v0
	v_mov_b32_e32 v72, v0
	v_mov_b32_e32 v73, v0
	v_mov_b32_e32 v74, v0
	v_mov_b32_e32 v75, v0
	v_mov_b32_e32 v76, v0
	v_mov_b32_e32 v77, v0
	v_mov_b32_e32 v78, v0
	v_mov_b32_e32 v79, v0
	v_mov_b32_e32 v80, v0
	v_mov_b32_e32 v81, v0
	v_mov_b32_e32 v82, v0
	v_mov_b32_e32 v83, v0
	v_mov_b32_e32 v84, v0
	v_mov_b32_e32 v85, v0
	v_mov_b32_e32 v86, v0
	v_mov_b32_e32 v87, v0
	v_mov_b32_e32 v88, v0
	v_mov_b32_e32 v89, v0
	v_mov_b32_e32 v90, v0
	v_mov_b32_e32 v91, v0
	v_mov_b32_e32 v92, v0
	v_mov_b32_e32 v93, v0
	v_mov_b32_e32 v94, v0
	v_mov_b32_e32 v95, v0
	v_mov_b32_e32 v96, v0
	v_mov_b32_e32 v97, v0
	v_mov_b32_e32 v98, v0
	v_mov_b32_e32 v99, v0
	v_mov_b32_e32 v100, v0
	v_mov_b32_e32 v101, v0
	v_mov_b32_e32 v102, v0
	v_mov_b32_e32 v103, v0
	v_mov_b32_e32 v104, v0
	v_mov_b32_e32 v105, v0
	v_mov_b32_e32 v106, v0
	v_mov_b32_e32 v107, v0
	v_mov_b32_e32 v108, v0
	v_mov_b32_e32 v109, v0
	v_mov_b32_e32 v110, v0
	v_mov_b32_e32 v111, v0
	v_mov_b32_e32 v112, v0
	v_mov_b32_e32 v113, v0
	v_mov_b32_e32 v114, v0
	v_mov_b32_e32 v115, v0
	v_mov_b32_e32 v116, v0
	v_mov_b32_e32 v117, v0
	v_mov_b32_e32 v118, v0
	v_mov_b32_e32 v119, v0
	v_mov_b32_e32 v120, v0
	v_mov_b32_e32 v121, v0
	v_mov_b32_e32 v122, v0
	v_mov_b32_e32 v123, v0
	v_mov_b32_e32 v124, v0
	v_mov_b32_e32 v125, v0
	v_mov_b32_e32 v126, v0
	v_mov_b32_e32 v127, v0
	s_waitcnt vmcnt(6)
	s_waitcnt lgkmcnt(0)
	v_readlane_b32 s44, v251, 5
	s_nop 0
	s_bitcmp1_b32 s44, 5
	s_cbranch_scc0 .Lnoprio_2
	s_setprio 2

.LBB0_123:
	s_lshl_b32 s2, s20, 10
	s_add_i32 s2, s15, s2
	v_readlane_b32 s72, v250, 53
	v_mov_b32_e32 v60, v200
	s_lshl_b64 s[8:9], s[2:3], 11
	v_readlane_b32 s80, v250, 61
	v_readlane_b32 s81, v250, 62
	v_ashrrev_i32_e32 v36, 3, v60
	v_lshlrev_b32_e32 v0, 3, v60
	s_add_u32 s8, s80, s8
	v_and_b32_e32 v181, 56, v0
	v_add_u32_e32 v42, 32, v36
	v_add_u32_e32 v48, 64, v36
	v_add_u32_e32 v54, 0x60, v36
	s_addc_u32 s9, s81, s9
	v_lshlrev_b32_e32 v196, 1, v181
	v_ashrrev_i32_e32 v37, 31, v36
	v_ashrrev_i32_e32 v43, 31, v42
	v_ashrrev_i32_e32 v49, 31, v48
	v_ashrrev_i32_e32 v55, 31, v54
	v_lshl_add_u64 v[128:129], s[6:7], 0, v[196:197]
	v_lshl_add_u64 v[130:131], s[8:9], 0, v[196:197]
	v_lshlrev_b64 v[132:133], 11, v[36:37]
	v_lshlrev_b64 v[134:135], 11, v[42:43]
	v_lshlrev_b64 v[136:137], 11, v[48:49]
	v_lshlrev_b64 v[138:139], 11, v[54:55]
	v_lshl_add_u64 v[38:39], v[128:129], 0, v[132:133]
	v_lshl_add_u64 v[40:41], v[130:131], 0, v[132:133]
	v_lshl_add_u64 v[44:45], v[128:129], 0, v[134:135]
	v_lshl_add_u64 v[46:47], v[130:131], 0, v[134:135]
	v_lshl_add_u64 v[50:51], v[128:129], 0, v[136:137]
	v_lshl_add_u64 v[52:53], v[130:131], 0, v[136:137]
	v_lshl_add_u64 v[56:57], v[128:129], 0, v[138:139]
	v_lshl_add_u64 v[58:59], v[130:131], 0, v[138:139]
	v_and_b32_e32 v242, 63, v200
	v_readfirstlane_b32 s41, v200
	v_lshrrev_b32_e32 v243, 3, v242
	v_and_b32_e32 v244, 7, v242
	v_lshrrev_b32_e32 v246, 4, v242
	s_lshr_b32 s41, s41, 6
	v_xor_b32_e32 v244, v244, v246
	v_lshlrev_b32_e32 v244, 4, v244
	v_xor_b32_e32 v246, 64, v244
	s_lshl_b32 s46, s41, 5
	v_add_u32_e32 v243, s46, v243
	v_lshlrev_b32_e32 v247, 11, v243
	v_add_u32_e32 v186, v247, v244
	v_add_u32_e32 v187, v247, v246
	v_add_u32_e32 v188, 0x8000, v186
	v_add_u32_e32 v189, 0x8000, v187
	v_add_u32_e32 v187, 0x4000, v187
	v_add_u32_e32 v189, 0x4000, v189
	v_and_b32_e32 v243, 31, v242
	v_lshrrev_b32_e32 v244, 5, v242
	v_bfe_u32 v246, v242, 1, 3
	v_xor_b32_e32 v244, v244, v246
	v_lshlrev_b32_e32 v244, 4, v244
	v_lshl_add_u32 v244, v243, 7, v244
	s_lshr_b32 s46, s41, 1
	s_lshl_b32 s46, s46, 13
	v_add_u32_e32 v190, s46, v244
	s_and_b32 s46, s41, 1
	s_lshl_b32 s46, s46, 13
	s_add_u32 s46, s46, 0x4000
	v_add_u32_e32 v194, s46, v244
	v_xor_b32_e32 v191, 32, v190
	v_xor_b32_e32 v201, 32, v194
	v_xor_b32_e32 v192, 64, v190
	v_xor_b32_e32 v206, 64, v194
	v_xor_b32_e32 v193, 96, v190
	v_xor_b32_e32 v214, 96, v194
	s_lshl_b32 s46, s41, 12
	s_add_u32 s47, s46, 0x4000
	s_mov_b32 s42, s6
	s_mov_b32 s43, s7
	s_mov_b32 s44, s8
	s_mov_b32 s45, s9
	s_add_u32 m0, s46, 0x0
	s_nop 0
	global_load_lds_dwordx4 v186, s[42:43]
	s_add_u32 m0, m0, 0x400
	s_nop 0
	global_load_lds_dwordx4 v187, s[42:43]
	s_add_u32 m0, m0, 0x400
	s_nop 0
	global_load_lds_dwordx4 v188, s[42:43]
	s_add_u32 m0, m0, 0x400
	s_nop 0
	global_load_lds_dwordx4 v189, s[42:43]
	s_add_u32 m0, s46, 0x4000
	s_nop 0
	global_load_lds_dwordx4 v186, s[44:45]
	s_add_u32 m0, m0, 0x400
	s_nop 0
	global_load_lds_dwordx4 v187, s[44:45]
	s_add_u32 m0, m0, 0x400
	s_nop 0
	global_load_lds_dwordx4 v188, s[44:45]
	s_add_u32 m0, m0, 0x400
	s_nop 0
	global_load_lds_dwordx4 v189, s[44:45]
	s_add_u32 s42, s42, 128
	s_addc_u32 s43, s43, 0
	s_add_u32 s44, s44, 128
	s_addc_u32 s45, s45, 0
	v_and_b32_e32 v61, 31, v60
	v_lshrrev_b32_e32 v62, 1, v60
	v_and_b32_e32 v60, 0x5f, v60
	s_movk_i32 s2, 0x90
	s_mov_b32 s26, 0xfffffc0
	v_and_or_b32 v61, v62, s26, v61
	v_and_b32_e32 v62, 16, v62
	v_mad_u32_u24 v60, v60, s2, 0
	v_mul_lo_u32 v63, v36, s2
	v_mul_lo_u32 v61, v61, s2
	v_add_u32_e32 v182, v60, v62
	v_add_u32_e32 v60, 0, v196
	v_lshlrev_b64 v[36:37], 10, v[36:37]
	v_add_u32_e32 v96, 0x1200, v63
	v_lshlrev_b64 v[42:43], 10, v[42:43]
	v_lshlrev_b64 v[48:49], 10, v[48:49]
	v_lshlrev_b64 v[54:55], 10, v[54:55]
	v_add_u32_e32 v38, 0, v61
	v_add_u32_e32 v183, v60, v63
	s_mov_b32 s21, 0
	s_movk_i32 s22, 0x80
	v_mov_b32_e32 v0, 0
	v_mov_b32_e32 v1, v172
	v_mov_b32_e32 v2, v172
	v_mov_b32_e32 v3, v172
	v_lshlrev_b64 v[140:141], 1, v[36:37]
	v_add_u32_e32 v184, v60, v96
	v_lshlrev_b64 v[142:143], 1, v[42:43]
	v_lshlrev_b64 v[144:145], 1, v[48:49]
	v_lshlrev_b64 v[146:147], 1, v[54:55]
	v_add_u32_e32 v185, v38, v62
	v_mov_b32_e32 v36, v172
	v_mov_b32_e32 v37, v172
	v_mov_b32_e32 v38, v172
	v_mov_b32_e32 v39, v172
	v_mov_b32_e32 v40, v172
	v_mov_b32_e32 v41, v172
	v_mov_b32_e32 v42, v172
	v_mov_b32_e32 v43, v172
	v_mov_b32_e32 v44, v172
	v_mov_b32_e32 v45, v172
	v_mov_b32_e32 v46, v172
	v_mov_b32_e32 v4, v172
	v_mov_b32_e32 v5, v172
	v_mov_b32_e32 v6, v172
	v_mov_b32_e32 v7, v172
	v_mov_b32_e32 v8, v172
	v_mov_b32_e32 v9, v172
	v_mov_b32_e32 v10, v172
	v_mov_b32_e32 v11, v172
	v_mov_b32_e32 v12, v172
	v_mov_b32_e32 v13, v172
	v_mov_b32_e32 v14, v172
	v_mov_b32_e32 v15, v172
	v_mov_b32_e32 v16, 0
	v_mov_b32_e32 v17, v172
	v_mov_b32_e32 v18, v172
	v_mov_b32_e32 v19, v172
	v_mov_b32_e32 v20, v172
	v_mov_b32_e32 v21, v172
	v_mov_b32_e32 v22, v172
	v_mov_b32_e32 v23, v172
	v_mov_b32_e32 v24, v172
	v_mov_b32_e32 v25, v172
	v_mov_b32_e32 v26, v172
	v_mov_b32_e32 v27, v172
	v_mov_b32_e32 v28, v172
	v_mov_b32_e32 v29, v172
	v_mov_b32_e32 v30, v172
	v_mov_b32_e32 v31, v172
	v_mov_b32_e32 v32, 0
	v_mov_b32_e32 v33, v172
	v_mov_b32_e32 v34, v172
	v_mov_b32_e32 v35, v172
	v_mov_b32_e32 v47, v172
	v_mov_b32_e32 v48, 0
	v_mov_b32_e32 v49, v172
	v_mov_b32_e32 v50, v172
	v_mov_b32_e32 v51, v172
	v_mov_b32_e32 v52, v172
	v_mov_b32_e32 v53, v172
	v_mov_b32_e32 v54, v172
	v_mov_b32_e32 v55, v172
	v_mov_b32_e32 v56, v172
	v_mov_b32_e32 v57, v172
	v_mov_b32_e32 v58, v172
	v_mov_b32_e32 v59, v172
	v_mov_b32_e32 v60, v172
	v_mov_b32_e32 v61, v172
	v_mov_b32_e32 v62, v172
	v_mov_b32_e32 v63, v172
	v_readlane_b32 s73, v250, 54
	v_readlane_b32 s74, v250, 55
	v_readlane_b32 s75, v250, 56
	v_readlane_b32 s76, v250, 57
	v_readlane_b32 s77, v250, 58
	v_readlane_b32 s78, v250, 59
	v_readlane_b32 s79, v250, 60
	v_readlane_b32 s82, v250, 63
	v_readlane_b32 s83, v249, 0
	v_readlane_b32 s84, v249, 1
	v_readlane_b32 s85, v249, 2
	v_readlane_b32 s86, v249, 3
	v_readlane_b32 s87, v249, 4
	s_mov_b32 s49, 0x8000
	s_waitcnt vmcnt(0)
	s_waitcnt lgkmcnt(0)
	v_readlane_b32 s41, v251, 5
	s_nop 0
	s_bitcmp1_b32 s41, 5
	s_cbranch_scc0 .Lnoprio_5
	s_setprio 2

.Lp4g_tail:
	ds_read_b128 v[64:67], v194
	ds_read_b128 v[68:71], v190
	ds_read_b128 v[72:75], v194 offset:4096
	ds_read_b128 v[76:79], v190 offset:4096
	ds_read_b128 v[80:83], v201
	ds_read_b128 v[84:87], v191
	ds_read_b128 v[88:91], v201 offset:4096
	ds_read_b128 v[92:95], v191 offset:4096
	ds_read_b128 v[96:99], v206
	ds_read_b128 v[100:103], v192
	ds_read_b128 v[104:107], v206 offset:4096
	ds_read_b128 v[108:111], v192 offset:4096
	ds_read_b128 v[112:115], v214
	ds_read_b128 v[116:119], v193
	ds_read_b128 v[120:123], v214 offset:4096
	ds_read_b128 v[124:127], v193 offset:4096
	s_waitcnt lgkmcnt(14)
	v_mfma_f32_32x32x16_bf16 v[48:63], v[64:67], v[68:71], v[48:63]
	s_waitcnt lgkmcnt(13)
	v_mfma_f32_32x32x16_bf16 v[32:47], v[72:75], v[68:71], v[32:47]
	s_waitcnt lgkmcnt(12)
	v_mfma_f32_32x32x16_bf16 v[16:31], v[64:67], v[76:79], v[16:31]
	v_mfma_f32_32x32x16_bf16 v[0:15], v[72:75], v[76:79], v[0:15]
	s_waitcnt lgkmcnt(10)
	v_mfma_f32_32x32x16_bf16 v[48:63], v[80:83], v[84:87], v[48:63]
	s_waitcnt lgkmcnt(9)
	v_mfma_f32_32x32x16_bf16 v[32:47], v[88:91], v[84:87], v[32:47]
	s_waitcnt lgkmcnt(8)
	v_mfma_f32_32x32x16_bf16 v[16:31], v[80:83], v[92:95], v[16:31]
	v_mfma_f32_32x32x16_bf16 v[0:15], v[88:91], v[92:95], v[0:15]
	s_waitcnt lgkmcnt(6)
	v_mfma_f32_32x32x16_bf16 v[48:63], v[96:99], v[100:103], v[48:63]
	s_waitcnt lgkmcnt(5)
	v_mfma_f32_32x32x16_bf16 v[32:47], v[104:107], v[100:103], v[32:47]
	s_waitcnt lgkmcnt(4)
	v_mfma_f32_32x32x16_bf16 v[16:31], v[96:99], v[108:111], v[16:31]
	v_mfma_f32_32x32x16_bf16 v[0:15], v[104:107], v[108:111], v[0:15]
	s_waitcnt lgkmcnt(2)
	v_mfma_f32_32x32x16_bf16 v[48:63], v[112:115], v[116:119], v[48:63]
	s_waitcnt lgkmcnt(1)
	v_mfma_f32_32x32x16_bf16 v[32:47], v[120:123], v[116:119], v[32:47]
	s_waitcnt lgkmcnt(0)
	v_mfma_f32_32x32x16_bf16 v[16:31], v[112:115], v[124:127], v[16:31]
	v_mfma_f32_32x32x16_bf16 v[0:15], v[120:123], v[124:127], v[0:15]
	v_xor_b32_e32 v190, 0x8000, v190
	v_xor_b32_e32 v191, 0x8000, v191
	v_xor_b32_e32 v192, 0x8000, v192
	v_xor_b32_e32 v193, 0x8000, v193
	v_xor_b32_e32 v194, 0x8000, v194
	v_xor_b32_e32 v201, 0x8000, v201
	v_xor_b32_e32 v206, 0x8000, v206
	v_xor_b32_e32 v214, 0x8000, v214
	s_add_u32 s21, s21, 1
	s_waitcnt vmcnt(0)
	s_cmp_lt_u32 s21, 16
	s_barrier
	s_setprio 0
	s_branch .LBB0_127

.LBB0_416:
	s_and_b32 s0, s0, 15
	s_or_b32 s18, s0, s50
	v_readlane_b32 s72, v250, 53
	s_lshl_b32 s0, s18, 18
	v_readlane_b32 s78, v250, 59
	v_readlane_b32 s79, v250, 60
	s_add_u32 s4, s78, s0
	v_mov_b32_e32 v3, v200
	v_readlane_b32 s80, v250, 61
	s_addc_u32 s5, s79, 0
	s_lshl_b32 s0, s17, 18
	v_ashrrev_i32_e32 v36, 3, v3
	v_lshlrev_b32_e32 v0, 3, v3
	v_readlane_b32 s81, v250, 62
	s_waitcnt vmcnt(0)
	v_and_b32_e32 v148, 56, v0
	s_add_u32 s6, s80, s0
	v_add_u32_e32 v40, 32, v36
	v_add_u32_e32 v44, 64, v36
	v_add_u32_e32 v48, 0x60, v36
	v_lshlrev_b32_e32 v196, 1, v148
	v_ashrrev_i32_e32 v37, 31, v36
	v_ashrrev_i32_e32 v41, 31, v40
	s_addc_u32 s7, s81, 0
	v_ashrrev_i32_e32 v45, 31, v44
	v_ashrrev_i32_e32 v49, 31, v48
	v_lshl_add_u64 v[128:129], s[4:5], 0, v[196:197]
	v_lshlrev_b64 v[130:131], 11, v[36:37]
	v_lshlrev_b64 v[132:133], 11, v[40:41]
	v_lshlrev_b64 v[134:135], 11, v[44:45]
	v_lshlrev_b64 v[136:137], 11, v[48:49]
	v_lshl_add_u64 v[138:139], s[6:7], 0, v[196:197]
	v_lshl_add_u64 v[38:39], v[128:129], 0, v[130:131]
	v_lshl_add_u64 v[42:43], v[128:129], 0, v[132:133]
	v_lshl_add_u64 v[46:47], v[128:129], 0, v[134:135]
	v_lshl_add_u64 v[50:51], v[128:129], 0, v[136:137]
	v_lshl_add_u64 v[52:53], v[138:139], 0, v[130:131]
	v_lshl_add_u64 v[54:55], v[138:139], 0, v[132:133]
	v_and_b32_e32 v184, 63, v200
	v_readfirstlane_b32 s2, v200
	v_lshrrev_b32_e32 v185, 3, v184
	v_and_b32_e32 v186, 7, v184
	v_lshrrev_b32_e32 v187, 4, v184
	s_lshr_b32 s2, s2, 6
	v_xor_b32_e32 v186, v186, v187
	v_lshlrev_b32_e32 v186, 4, v186
	v_xor_b32_e32 v187, 64, v186
	s_lshl_b32 s32, s2, 5
	v_add_u32_e32 v185, s32, v185
	v_lshlrev_b32_e32 v188, 11, v185
	v_add_u32_e32 v166, v188, v186
	v_add_u32_e32 v167, v188, v187
	v_add_u32_e32 v168, 0x8000, v166
	v_add_u32_e32 v169, 0x8000, v167
	v_add_u32_e32 v167, 0x4000, v167
	v_add_u32_e32 v169, 0x4000, v169
	v_and_b32_e32 v185, 31, v184
	v_lshrrev_b32_e32 v186, 5, v184
	v_bfe_u32 v187, v184, 1, 3
	v_xor_b32_e32 v186, v186, v187
	v_lshlrev_b32_e32 v186, 4, v186
	v_lshl_add_u32 v186, v185, 7, v186
	s_lshr_b32 s32, s2, 1
	s_lshl_b32 s32, s32, 13
	v_add_u32_e32 v170, s32, v186
	s_and_b32 s32, s2, 1
	s_lshl_b32 s32, s32, 13
	s_add_u32 s32, s32, 0x4000
	v_add_u32_e32 v174, s32, v186
	v_xor_b32_e32 v171, 32, v170
	v_xor_b32_e32 v175, 32, v174
	v_xor_b32_e32 v172, 64, v170
	v_xor_b32_e32 v176, 64, v174
	v_xor_b32_e32 v173, 96, v170
	v_xor_b32_e32 v177, 96, v174
	s_lshl_b32 s32, s2, 12
	s_add_u32 s49, s32, 0x4000
	s_mov_b32 s8, s4
	s_mov_b32 s9, s5
	s_mov_b32 s46, s6
	s_mov_b32 s47, s7
	s_add_u32 m0, s32, 0x0
	s_nop 0
	global_load_lds_dwordx4 v166, s[8:9]
	s_add_u32 m0, m0, 0x400
	s_nop 0
	global_load_lds_dwordx4 v167, s[8:9]
	s_add_u32 m0, m0, 0x400
	s_nop 0
	global_load_lds_dwordx4 v168, s[8:9]
	s_add_u32 m0, m0, 0x400
	s_nop 0
	global_load_lds_dwordx4 v169, s[8:9]
	s_add_u32 m0, s32, 0x4000
	s_nop 0
	global_load_lds_dwordx4 v166, s[46:47]
	s_add_u32 m0, m0, 0x400
	s_nop 0
	global_load_lds_dwordx4 v167, s[46:47]
	s_add_u32 m0, m0, 0x400
	s_nop 0
	global_load_lds_dwordx4 v168, s[46:47]
	s_add_u32 m0, m0, 0x400
	s_nop 0
	global_load_lds_dwordx4 v169, s[46:47]
	s_add_u32 s8, s8, 128
	s_addc_u32 s9, s9, 0
	s_add_u32 s46, s46, 128
	s_addc_u32 s47, s47, 0
	v_lshl_add_u64 v[56:57], v[138:139], 0, v[134:135]
	v_lshl_add_u64 v[58:59], v[138:139], 0, v[136:137]
	v_and_b32_e32 v60, 31, v3
	v_lshrrev_b32_e32 v61, 1, v3
	v_and_b32_e32 v3, 0x5f, v3
	s_movk_i32 s2, 0x90
	v_and_or_b32 v60, v61, s23, v60
	v_and_b32_e32 v61, 16, v61
	v_mad_u32_u24 v3, v3, s2, 0
	v_mul_lo_u32 v62, v36, s2
	v_mul_lo_u32 v60, v60, s2
	v_add_u32_e32 v149, v3, v61
	v_add_u32_e32 v3, 0, v196
	v_mov_b32_e32 v0, 0
	v_add_u32_e32 v63, 0x1200, v62
	v_lshlrev_b64 v[36:37], 10, v[36:37]
	v_lshlrev_b64 v[40:41], 10, v[40:41]
	v_lshlrev_b64 v[44:45], 10, v[44:45]
	v_lshlrev_b64 v[48:49], 10, v[48:49]
	v_add_u32_e32 v60, 0, v60
	v_add_u32_e32 v150, v3, v62
	s_movk_i32 s0, 0x80
	s_mov_b32 s1, 0
	v_mov_b32_e32 v1, v0
	v_mov_b32_e32 v2, v0
	v_lshlrev_b64 v[140:141], 1, v[36:37]
	v_add_u32_e32 v151, v3, v63
	v_lshlrev_b64 v[142:143], 1, v[40:41]
	v_lshlrev_b64 v[144:145], 1, v[44:45]
	v_lshlrev_b64 v[146:147], 1, v[48:49]
	v_add_u32_e32 v152, v60, v61
	v_mov_b32_e32 v3, v0
	v_mov_b32_e32 v36, v0
	v_mov_b32_e32 v37, v0
	v_mov_b32_e32 v38, v0
	v_mov_b32_e32 v39, v0
	v_mov_b32_e32 v40, v0
	v_mov_b32_e32 v41, v0
	v_mov_b32_e32 v42, v0
	v_mov_b32_e32 v43, v0
	v_mov_b32_e32 v44, v0
	v_mov_b32_e32 v45, v0
	v_mov_b32_e32 v46, v0
	v_mov_b32_e32 v47, v0
	v_mov_b32_e32 v4, v0
	v_mov_b32_e32 v5, v0
	v_mov_b32_e32 v6, v0
	v_mov_b32_e32 v7, v0
	v_mov_b32_e32 v8, v0
	v_mov_b32_e32 v9, v0
	v_mov_b32_e32 v10, v0
	v_mov_b32_e32 v11, v0
	v_mov_b32_e32 v12, v0
	v_mov_b32_e32 v13, v0
	v_mov_b32_e32 v14, v0
	v_mov_b32_e32 v15, v0
	v_mov_b32_e32 v16, v0
	v_mov_b32_e32 v17, v0
	v_mov_b32_e32 v18, v0
	v_mov_b32_e32 v19, v0
	v_mov_b32_e32 v20, v0
	v_mov_b32_e32 v21, v0
	v_mov_b32_e32 v22, v0
	v_mov_b32_e32 v23, v0
	v_mov_b32_e32 v24, v0
	v_mov_b32_e32 v25, v0
	v_mov_b32_e32 v26, v0
	v_mov_b32_e32 v27, v0
	v_mov_b32_e32 v28, v0
	v_mov_b32_e32 v29, v0
	v_mov_b32_e32 v30, v0
	v_mov_b32_e32 v31, v0
	v_mov_b32_e32 v32, v0
	v_mov_b32_e32 v33, v0
	v_mov_b32_e32 v34, v0
	v_mov_b32_e32 v35, v0
	v_mov_b32_e32 v48, v0
	v_mov_b32_e32 v49, v0
	v_mov_b32_e32 v50, v0
	v_mov_b32_e32 v51, v0
	v_mov_b32_e32 v52, v0
	v_mov_b32_e32 v53, v0
	v_mov_b32_e32 v54, v0
	v_mov_b32_e32 v55, v0
	v_mov_b32_e32 v56, v0
	v_mov_b32_e32 v57, v0
	v_mov_b32_e32 v58, v0
	v_mov_b32_e32 v59, v0
	v_mov_b32_e32 v60, v0
	v_mov_b32_e32 v61, v0
	v_mov_b32_e32 v62, v0
	v_mov_b32_e32 v63, v0
	v_readlane_b32 s73, v250, 54
	v_readlane_b32 s74, v250, 55
	v_readlane_b32 s75, v250, 56
	v_readlane_b32 s76, v250, 57
	v_readlane_b32 s77, v250, 58
	v_readlane_b32 s82, v250, 63
	v_readlane_b32 s83, v249, 0
	v_readlane_b32 s84, v249, 1
	v_readlane_b32 s85, v249, 2
	v_readlane_b32 s86, v249, 3
	v_readlane_b32 s87, v249, 4
	s_mov_b32 s0, 0x8000
	s_waitcnt vmcnt(0)
	s_waitcnt lgkmcnt(0)
	v_readlane_b32 s2, v251, 5
	s_nop 0
	s_bitcmp1_b32 s2, 5
	s_cbranch_scc0 .Lnoprio_3
	s_setprio 2

.Lp1z_tail:
	ds_read_b128 v[64:67], v174
	ds_read_b128 v[68:71], v170
	ds_read_b128 v[72:75], v174 offset:4096
	ds_read_b128 v[76:79], v170 offset:4096
	ds_read_b128 v[80:83], v175
	ds_read_b128 v[84:87], v171
	ds_read_b128 v[88:91], v175 offset:4096
	ds_read_b128 v[92:95], v171 offset:4096
	ds_read_b128 v[96:99], v176
	ds_read_b128 v[100:103], v172
	ds_read_b128 v[104:107], v176 offset:4096
	ds_read_b128 v[108:111], v172 offset:4096
	ds_read_b128 v[112:115], v177
	ds_read_b128 v[116:119], v173
	ds_read_b128 v[120:123], v177 offset:4096
	ds_read_b128 v[124:127], v173 offset:4096
	s_waitcnt lgkmcnt(14)
	v_mfma_f32_32x32x16_bf16 v[48:63], v[64:67], v[68:71], v[48:63]
	s_waitcnt lgkmcnt(13)
	v_mfma_f32_32x32x16_bf16 v[32:47], v[72:75], v[68:71], v[32:47]
	s_waitcnt lgkmcnt(12)
	v_mfma_f32_32x32x16_bf16 v[16:31], v[64:67], v[76:79], v[16:31]
	v_mfma_f32_32x32x16_bf16 v[0:15], v[72:75], v[76:79], v[0:15]
	s_waitcnt lgkmcnt(10)
	v_mfma_f32_32x32x16_bf16 v[48:63], v[80:83], v[84:87], v[48:63]
	s_waitcnt lgkmcnt(9)
	v_mfma_f32_32x32x16_bf16 v[32:47], v[88:91], v[84:87], v[32:47]
	s_waitcnt lgkmcnt(8)
	v_mfma_f32_32x32x16_bf16 v[16:31], v[80:83], v[92:95], v[16:31]
	v_mfma_f32_32x32x16_bf16 v[0:15], v[88:91], v[92:95], v[0:15]
	s_waitcnt lgkmcnt(6)
	v_mfma_f32_32x32x16_bf16 v[48:63], v[96:99], v[100:103], v[48:63]
	s_waitcnt lgkmcnt(5)
	v_mfma_f32_32x32x16_bf16 v[32:47], v[104:107], v[100:103], v[32:47]
	s_waitcnt lgkmcnt(4)
	v_mfma_f32_32x32x16_bf16 v[16:31], v[96:99], v[108:111], v[16:31]
	v_mfma_f32_32x32x16_bf16 v[0:15], v[104:107], v[108:111], v[0:15]
	s_waitcnt lgkmcnt(2)
	v_mfma_f32_32x32x16_bf16 v[48:63], v[112:115], v[116:119], v[48:63]
	s_waitcnt lgkmcnt(1)
	v_mfma_f32_32x32x16_bf16 v[32:47], v[120:123], v[116:119], v[32:47]
	s_waitcnt lgkmcnt(0)
	v_mfma_f32_32x32x16_bf16 v[16:31], v[112:115], v[124:127], v[16:31]
	v_mfma_f32_32x32x16_bf16 v[0:15], v[120:123], v[124:127], v[0:15]
	v_xor_b32_e32 v170, 0x8000, v170
	v_xor_b32_e32 v171, 0x8000, v171
	v_xor_b32_e32 v172, 0x8000, v172
	v_xor_b32_e32 v173, 0x8000, v173
	v_xor_b32_e32 v174, 0x8000, v174
	v_xor_b32_e32 v175, 0x8000, v175
	v_xor_b32_e32 v176, 0x8000, v176
	v_xor_b32_e32 v177, 0x8000, v177
	s_add_u32 s1, s1, 1
	s_waitcnt vmcnt(0)
	s_cmp_lt_u32 s1, 16
	s_barrier
	s_setprio 0
	s_branch .LBB0_420

.LBB0_448:
	s_ashr_i32 s6, s12, 3
	s_ashr_i32 s7, s6, 31
	s_and_b32 s1, s12, 7
	s_lshl_b64 s[4:5], s[6:7], 17
	s_lshl_b64 s[6:7], s[6:7], 18
	s_add_u32 s6, s56, s6
	v_readlane_b32 s16, v250, 53
	v_mov_b32_e32 v1, v200
	s_addc_u32 s7, s57, s7
	s_lshl_b32 s2, s1, 18
	v_readlane_b32 s30, v249, 3
	v_readlane_b32 s31, v249, 4
	v_ashrrev_i32_e32 v34, 3, v1
	v_lshlrev_b32_e32 v0, 3, v1
	s_add_u32 s8, s30, s2
	s_waitcnt vmcnt(0)
	v_and_b32_e32 v148, 56, v0
	v_add_u32_e32 v40, 32, v34
	v_add_u32_e32 v46, 64, v34
	v_add_u32_e32 v50, 0x60, v34
	s_addc_u32 s9, s31, 0
	v_lshlrev_b32_e32 v196, 1, v148
	v_ashrrev_i32_e32 v35, 31, v34
	v_ashrrev_i32_e32 v41, 31, v40
	v_ashrrev_i32_e32 v47, 31, v46
	v_ashrrev_i32_e32 v51, 31, v50
	v_lshl_add_u64 v[128:129], s[6:7], 0, v[196:197]
	v_lshl_add_u64 v[130:131], s[8:9], 0, v[196:197]
	v_lshlrev_b64 v[132:133], 11, v[34:35]
	v_lshlrev_b64 v[134:135], 11, v[40:41]
	v_lshlrev_b64 v[136:137], 11, v[46:47]
	v_lshlrev_b64 v[138:139], 11, v[50:51]
	v_lshl_add_u64 v[36:37], v[128:129], 0, v[132:133]
	v_lshl_add_u64 v[38:39], v[130:131], 0, v[132:133]
	v_lshl_add_u64 v[42:43], v[128:129], 0, v[134:135]
	v_lshl_add_u64 v[44:45], v[130:131], 0, v[134:135]
	v_lshl_add_u64 v[48:49], v[128:129], 0, v[136:137]
	v_lshl_add_u64 v[52:53], v[128:129], 0, v[138:139]
	v_lshl_add_u64 v[54:55], v[130:131], 0, v[136:137]
	v_lshl_add_u64 v[56:57], v[130:131], 0, v[138:139]
	v_and_b32_e32 v184, 63, v200
	v_readfirstlane_b32 s2, v200
	v_lshrrev_b32_e32 v185, 3, v184
	v_and_b32_e32 v186, 7, v184
	v_lshrrev_b32_e32 v187, 4, v184
	s_lshr_b32 s2, s2, 6
	v_xor_b32_e32 v186, v186, v187
	v_lshlrev_b32_e32 v186, 4, v186
	v_xor_b32_e32 v187, 64, v186
	s_lshl_b32 s32, s2, 5
	v_add_u32_e32 v185, s32, v185
	v_lshlrev_b32_e32 v188, 11, v185
	v_add_u32_e32 v166, v188, v186
	v_add_u32_e32 v167, v188, v187
	v_add_u32_e32 v168, 0x8000, v166
	v_add_u32_e32 v169, 0x8000, v167
	v_add_u32_e32 v167, 0x4000, v167
	v_add_u32_e32 v169, 0x4000, v169
	v_and_b32_e32 v185, 31, v184
	v_lshrrev_b32_e32 v186, 5, v184
	v_bfe_u32 v187, v184, 1, 3
	v_xor_b32_e32 v186, v186, v187
	v_lshlrev_b32_e32 v186, 4, v186
	v_lshl_add_u32 v186, v185, 7, v186
	s_lshr_b32 s32, s2, 1
	s_lshl_b32 s32, s32, 13
	v_add_u32_e32 v170, s32, v186
	s_and_b32 s32, s2, 1
	s_lshl_b32 s32, s32, 13
	s_add_u32 s32, s32, 0x4000
	v_add_u32_e32 v174, s32, v186
	v_xor_b32_e32 v171, 32, v170
	v_xor_b32_e32 v175, 32, v174
	v_xor_b32_e32 v172, 64, v170
	v_xor_b32_e32 v176, 64, v174
	v_xor_b32_e32 v173, 96, v170
	v_xor_b32_e32 v177, 96, v174
	s_lshl_b32 s32, s2, 12
	s_add_u32 s49, s32, 0x4000
	s_mov_b32 s10, s6
	s_mov_b32 s11, s7
	s_mov_b32 s46, s8
	s_mov_b32 s47, s9
	s_add_u32 m0, s32, 0x0
	s_nop 0
	global_load_lds_dwordx4 v166, s[10:11]
	s_add_u32 m0, m0, 0x400
	s_nop 0
	global_load_lds_dwordx4 v167, s[10:11]
	s_add_u32 m0, m0, 0x400
	s_nop 0
	global_load_lds_dwordx4 v168, s[10:11]
	s_add_u32 m0, m0, 0x400
	s_nop 0
	global_load_lds_dwordx4 v169, s[10:11]
	s_add_u32 m0, s32, 0x4000
	s_nop 0
	global_load_lds_dwordx4 v166, s[46:47]
	s_add_u32 m0, m0, 0x400
	s_nop 0
	global_load_lds_dwordx4 v167, s[46:47]
	s_add_u32 m0, m0, 0x400
	s_nop 0
	global_load_lds_dwordx4 v168, s[46:47]
	s_add_u32 m0, m0, 0x400
	s_nop 0
	global_load_lds_dwordx4 v169, s[46:47]
	s_add_u32 s10, s10, 128
	s_addc_u32 s11, s11, 0
	s_add_u32 s46, s46, 128
	s_addc_u32 s47, s47, 0
	v_and_b32_e32 v58, 31, v1
	v_lshrrev_b32_e32 v59, 1, v1
	v_and_b32_e32 v1, 0x5f, v1
	s_movk_i32 s2, 0x90
	v_and_or_b32 v58, v59, s10, v58
	v_and_b32_e32 v59, 16, v59
	v_mad_u32_u24 v1, v1, s2, 0
	v_mul_lo_u32 v60, v34, s2
	v_mul_lo_u32 v58, v58, s2
	v_add_u32_e32 v149, v1, v59
	v_add_u32_e32 v1, 0, v196
	v_mov_b32_e32 v0, 0
	v_lshlrev_b64 v[34:35], 10, v[34:35]
	v_add_u32_e32 v61, 0x1200, v60
	v_lshlrev_b64 v[40:41], 10, v[40:41]
	v_lshlrev_b64 v[46:47], 10, v[46:47]
	v_lshlrev_b64 v[50:51], 10, v[50:51]
	v_add_u32_e32 v58, 0, v58
	v_add_u32_e32 v150, v1, v60
	s_mov_b32 s13, 0
	s_movk_i32 s14, 0x80
	v_lshlrev_b64 v[140:141], 1, v[34:35]
	v_add_u32_e32 v151, v1, v61
	v_lshlrev_b64 v[142:143], 1, v[40:41]
	v_lshlrev_b64 v[144:145], 1, v[46:47]
	v_lshlrev_b64 v[146:147], 1, v[50:51]
	v_add_u32_e32 v152, v58, v59
	v_mov_b32_e32 v1, v0
	v_mov_b32_e32 v34, v0
	v_mov_b32_e32 v35, v0
	v_mov_b32_e32 v36, v0
	v_mov_b32_e32 v37, v0
	v_mov_b32_e32 v38, v0
	v_mov_b32_e32 v39, v0
	v_mov_b32_e32 v40, v0
	v_mov_b32_e32 v41, v0
	v_mov_b32_e32 v42, v0
	v_mov_b32_e32 v43, v0
	v_mov_b32_e32 v2, v0
	v_mov_b32_e32 v3, v0
	v_mov_b32_e32 v4, v0
	v_mov_b32_e32 v5, v0
	v_mov_b32_e32 v6, v0
	v_mov_b32_e32 v7, v0
	v_mov_b32_e32 v8, v0
	v_mov_b32_e32 v9, v0
	v_mov_b32_e32 v10, v0
	v_mov_b32_e32 v11, v0
	v_mov_b32_e32 v12, v0
	v_mov_b32_e32 v13, v0
	v_mov_b32_e32 v14, v0
	v_mov_b32_e32 v15, v0
	v_mov_b32_e32 v16, v0
	v_mov_b32_e32 v17, v0
	v_mov_b32_e32 v18, v0
	v_mov_b32_e32 v19, v0
	v_mov_b32_e32 v20, v0
	v_mov_b32_e32 v21, v0
	v_mov_b32_e32 v22, v0
	v_mov_b32_e32 v23, v0
	v_mov_b32_e32 v24, v0
	v_mov_b32_e32 v25, v0
	v_mov_b32_e32 v26, v0
	v_mov_b32_e32 v27, v0
	v_mov_b32_e32 v28, v0
	v_mov_b32_e32 v29, v0
	v_mov_b32_e32 v30, v0
	v_mov_b32_e32 v31, v0
	v_mov_b32_e32 v32, v0
	v_mov_b32_e32 v33, v0
	v_mov_b32_e32 v44, v0
	v_mov_b32_e32 v45, v0
	v_mov_b32_e32 v46, v0
	v_mov_b32_e32 v47, v0
	v_mov_b32_e32 v48, v0
	v_mov_b32_e32 v49, v0
	v_mov_b32_e32 v50, v0
	v_mov_b32_e32 v51, v0
	v_mov_b32_e32 v52, v0
	v_mov_b32_e32 v53, v0
	v_mov_b32_e32 v54, v0
	v_mov_b32_e32 v55, v0
	v_mov_b32_e32 v56, v0
	v_mov_b32_e32 v57, v0
	v_mov_b32_e32 v58, v0
	v_mov_b32_e32 v59, v0
	v_mov_b32_e32 v60, v0
	v_mov_b32_e32 v61, v0
	v_mov_b32_e32 v62, v0
	v_mov_b32_e32 v63, v0
	s_mov_b32 s15, 0xfffffc0
	v_readlane_b32 s17, v250, 54
	v_readlane_b32 s18, v250, 55
	v_readlane_b32 s19, v250, 56
	v_readlane_b32 s20, v250, 57
	v_readlane_b32 s21, v250, 58
	v_readlane_b32 s22, v250, 59
	v_readlane_b32 s23, v250, 60
	v_readlane_b32 s24, v250, 61
	v_readlane_b32 s25, v250, 62
	v_readlane_b32 s26, v250, 63
	v_readlane_b32 s27, v249, 0
	v_readlane_b32 s28, v249, 1
	v_readlane_b32 s29, v249, 2
	s_mov_b32 s14, 0x8000
	s_waitcnt vmcnt(0)
	s_waitcnt lgkmcnt(0)
	v_readlane_b32 s2, v251, 5
	s_nop 0
	s_bitcmp1_b32 s2, 5
	s_cbranch_scc0 .Lnoprio_4
	s_setprio 2

.Lp1k_tail:
	ds_read_b128 v[64:67], v174
	ds_read_b128 v[68:71], v170
	ds_read_b128 v[72:75], v174 offset:4096
	ds_read_b128 v[76:79], v170 offset:4096
	ds_read_b128 v[80:83], v175
	ds_read_b128 v[84:87], v171
	ds_read_b128 v[88:91], v175 offset:4096
	ds_read_b128 v[92:95], v171 offset:4096
	ds_read_b128 v[96:99], v176
	ds_read_b128 v[100:103], v172
	ds_read_b128 v[104:107], v176 offset:4096
	ds_read_b128 v[108:111], v172 offset:4096
	ds_read_b128 v[112:115], v177
	ds_read_b128 v[116:119], v173
	ds_read_b128 v[120:123], v177 offset:4096
	ds_read_b128 v[124:127], v173 offset:4096
	s_waitcnt lgkmcnt(14)
	v_mfma_f32_32x32x16_bf16 v[48:63], v[64:67], v[68:71], v[48:63]
	s_waitcnt lgkmcnt(13)
	v_mfma_f32_32x32x16_bf16 v[32:47], v[72:75], v[68:71], v[32:47]
	s_waitcnt lgkmcnt(12)
	v_mfma_f32_32x32x16_bf16 v[16:31], v[64:67], v[76:79], v[16:31]
	v_mfma_f32_32x32x16_bf16 v[0:15], v[72:75], v[76:79], v[0:15]
	s_waitcnt lgkmcnt(10)
	v_mfma_f32_32x32x16_bf16 v[48:63], v[80:83], v[84:87], v[48:63]
	s_waitcnt lgkmcnt(9)
	v_mfma_f32_32x32x16_bf16 v[32:47], v[88:91], v[84:87], v[32:47]
	s_waitcnt lgkmcnt(8)
	v_mfma_f32_32x32x16_bf16 v[16:31], v[80:83], v[92:95], v[16:31]
	v_mfma_f32_32x32x16_bf16 v[0:15], v[88:91], v[92:95], v[0:15]
	s_waitcnt lgkmcnt(6)
	v_mfma_f32_32x32x16_bf16 v[48:63], v[96:99], v[100:103], v[48:63]
	s_waitcnt lgkmcnt(5)
	v_mfma_f32_32x32x16_bf16 v[32:47], v[104:107], v[100:103], v[32:47]
	s_waitcnt lgkmcnt(4)
	v_mfma_f32_32x32x16_bf16 v[16:31], v[96:99], v[108:111], v[16:31]
	v_mfma_f32_32x32x16_bf16 v[0:15], v[104:107], v[108:111], v[0:15]
	s_waitcnt lgkmcnt(2)
	v_mfma_f32_32x32x16_bf16 v[48:63], v[112:115], v[116:119], v[48:63]
	s_waitcnt lgkmcnt(1)
	v_mfma_f32_32x32x16_bf16 v[32:47], v[120:123], v[116:119], v[32:47]
	s_waitcnt lgkmcnt(0)
	v_mfma_f32_32x32x16_bf16 v[16:31], v[112:115], v[124:127], v[16:31]
	v_mfma_f32_32x32x16_bf16 v[0:15], v[120:123], v[124:127], v[0:15]
	v_xor_b32_e32 v170, 0x8000, v170
	v_xor_b32_e32 v171, 0x8000, v171
	v_xor_b32_e32 v172, 0x8000, v172
	v_xor_b32_e32 v173, 0x8000, v173
	v_xor_b32_e32 v174, 0x8000, v174
	v_xor_b32_e32 v175, 0x8000, v175
	v_xor_b32_e32 v176, 0x8000, v176
	v_xor_b32_e32 v177, 0x8000, v177
	s_add_u32 s13, s13, 1
	s_waitcnt vmcnt(0)
	s_cmp_lt_u32 s13, 16
	s_barrier
	s_setprio 0
	s_branch .LBB0_447
